# combined: v53 + attention role-B deferred softmax + role-A priority 0 in PV + epilogue round pipelining (PH14a r2-4, PH3 r4)
# baseline (speedup 1.0000x reference)
; #define PG8_BAR __builtin_amdgcn_s_barrier()
; template <class Epi>
; __device__ __forceinline__ void gemm_phase(LAS unsigned char* lds, const Gemm g, const StaticOrder& S, const Epi& E, const int wid) {
;     ...
;         if (!has_next) break;
; #pragma unroll
;         for (int a = 0; a < 2; ++a)
; #pragma unroll
;             for (int b = 0; b < 2; ++b)
; #pragma unroll
;                 for (int m = 0; m < 4; ++m)
; #pragma unroll
;                     for (int n = 0; n < 2; ++n) acc[a][b][m][n] = (f32x4){0.f, 0.f, 0.f, 0.f};
;         cur = nxt; cA = nA; cB = nB; ++ui;
;         if (wr == 1) PG8_BAR;
;     }
.LBB0_716:
	s_or_b64 exec, exec, s[8:9]
	s_andn2_b64 vcc, exec, s[6:7]
	s_mov_b64 s[6:7], -1
	s_cbranch_vccnz .LBB0_657

; #define PG8_BAR __builtin_amdgcn_s_barrier()
; template <class Epi>
; __device__ __forceinline__ void gemm_phase(LAS unsigned char* lds, const Gemm g, const StaticOrder& S, const Epi& E, const int wid) {
;     ...
;         if (wr == 0) PG8_BAR;
;         E(acc, cur, wid);
;         if (!has_next) break;
; #pragma unroll
;         for (int a = 0; a < 2; ++a)
; #pragma unroll
;             for (int b = 0; b < 2; ++b)
; #pragma unroll
;                 for (int m = 0; m < 4; ++m)
; #pragma unroll
;                     for (int n = 0; n < 2; ++n) acc[a][b][m][n] = (f32x4){0.f, 0.f, 0.f, 0.f};
;         cur = nxt; cA = nA; cB = nB; ++ui;
;         if (wr == 1) PG8_BAR;
;     }
	s_andn2_b64 vcc, exec, s[0:1]
	s_cbranch_vccnz .LBB0_656
	s_barrier
	s_branch .LBB0_656
